# x warm-up moved to the end of the layer-0 attention phase (idle tail of early finishers)
# baseline (speedup 1.0000x reference)
.LBB0_705:
	v_readlane_b32 s0, v255, 19
	v_readlane_b32 s40, v252, 11
	s_waitcnt lgkmcnt(0)
	s_add_i32 s5, s0, 1
	s_cmp_lg_u32 s0, 5
	s_cbranch_scc1 .Lwarm_skip
	v_readlane_b32 s42, v252, 20
	v_readlane_b32 s43, v252, 21
	v_readlane_b32 s44, v252, 0
	s_sub_u32 s42, s42, 0x1c0
	s_subb_u32 s43, s43, 0
	s_load_dwordx2 s[42:43], s[42:43], 0x0
	s_lshl_b32 s44, s44, 17
	v_lshlrev_b32_e32 v60, 7, v220
	v_add_u32_e32 v60, s44, v60
	s_waitcnt lgkmcnt(0)
	s_nop 0
	global_load_dword v61, v60, s[42:43]
	v_add_u32_e32 v62, 0x8000, v60
	global_load_dword v63, v62, s[42:43]
	v_add_u32_e32 v60, 0x10000, v60
	global_load_dword v61, v60, s[42:43]
	v_add_u32_e32 v62, 0x10000, v62
	global_load_dword v63, v62, s[42:43]
	s_waitcnt vmcnt(0)
